# GEMM3 K-loop: leading wave half defers vmcnt(8) to the post-MFMA barrier; plus dtype comment line
# baseline (speedup 1.0000x reference)
; #define PG8_STAGE(bufoff, gbase, voff) do { _Pragma("unroll") for (int _i = 0; _i < 2; ++_i) \
;         __builtin_amdgcn_global_load_lds((const unsigned*)((const char*)(gbase) + (voff)[_i]), (PG8_LAS unsigned*)(lds + (bufoff) + ldsw + _i * 8192), 16, 0, 0); } while (0)
; #define PG8_LDA(dst, b, h) do { _Pragma("unroll") for (int m = 0; m < 4; ++m) _Pragma("unroll") for (int k = 0; k < 2; ++k) dst[m][k] = *(const PG8_LAS bf16x8*)(lds + PG8_SA(b, h) + aoff + m * 2048 + k * 1024); } while (0)
; #define PG8_LDB(dst, b, h) do { _Pragma("unroll") for (int n = 0; n < 2; ++n) _Pragma("unroll") for (int k = 0; k < 2; ++k) dst[n][k] = *(const PG8_LAS bf16x8*)(lds + PG8_SB(b, h) + boff + n * 2048 + k * 1024); } while (0)
; #define PG8_MMA(ai, bj, At, Bt) do { __builtin_amdgcn_s_setprio(1); _Pragma("unroll") for (int m = 0; m < 4; ++m) _Pragma("unroll") for (int n = 0; n < 2; ++n) _Pragma("unroll") for (int k = 0; k < 2; ++k) \
;         acc[ai][bj][m][n] = __builtin_amdgcn_mfma_f32_16x16x32_bf16(Bt[n][k], At[m][k], acc[ai][bj][m][n], 0, 0, 0); __builtin_amdgcn_s_setprio(0); } while (0)
; #define PG8_WAIT_V(n) asm volatile("s_waitcnt vmcnt(" #n ")" ::: "memory")
; #define PG8_WAIT_L(n) asm volatile("s_waitcnt lgkmcnt(" #n ")" ::: "memory")
; #define PG8_BAR __builtin_amdgcn_s_barrier()
; #define PG8_SCHED __builtin_amdgcn_sched_barrier(0)
; template <class Epi, class Sched, bool ALIGN_EPI = false, bool SP2 = false>
; __device__ __forceinline__ void gemm_phase(PG8_LAS unsigned char* lds, const Gemm g, const Sched& S, const Epi& E) {
;     ...
;             PG8_LDB(B0, 0, 0); PG8_LDB(B1, 0, 1); PG8_SCHED; PG8_LDA(At, 0, 0); PG8_STAGE(PG8_SA(1, 1), a1 + hstep, voffA);
;             PG8_WAIT_V(8); PG8_WAIT_L(0); PG8_BAR; PG8_MMA(0, 0, At, B0); PG8_MMA(0, 1, At, B1); PG8_BAR; PG8_SCHED;
.LBB0_1071:
	ds_read_b128 v[148:151], v162
	ds_read_b128 v[170:173], v162 offset:1024
	ds_read_b128 v[174:177], v162 offset:2048
	ds_read_b128 v[178:181], v162 offset:3072
	ds_read_b128 v[184:187], v163
	ds_read_b128 v[188:191], v163 offset:1024
	ds_read_b128 v[192:195], v163 offset:2048
	ds_read_b128 v[196:199], v163 offset:3072
	s_add_u32 s34, s30, 0xfff80080
	s_addc_u32 s35, s31, -1
	s_cmp_eq_u32 s58, 28
	s_cselect_b32 s37, s21, s35
	s_cselect_b32 s36, s29, s34
	s_cselect_b32 s35, s19, s57
	s_cselect_b32 s34, s55, s56
	v_lshl_add_u64 v[152:153], s[30:31], 0, v[140:141]
	s_add_i32 m0, s27, 0xc000
	ds_read_b128 v[200:203], v164
	ds_read_b128 v[204:207], v164 offset:1024
	ds_read_b128 v[208:211], v164 offset:2048
	ds_read_b128 v[212:215], v164 offset:3072
	ds_read_b128 v[216:219], v164 offset:4096
	ds_read_b128 v[220:223], v164 offset:5120
	ds_read_b128 v[224:227], v164 offset:6144
	ds_read_b128 v[228:231], v164 offset:7168
	global_load_lds_dwordx4 v[152:153], off
	v_lshl_add_u64 v[152:153], s[30:31], 0, v[142:143]
	s_add_i32 m0, s27, 0xe000
	s_nop 0
	global_load_lds_dwordx4 v[152:153], off
	s_and_b64 vcc, exec, s[16:17]
	s_cbranch_vccnz .Ldw_g1071_a0
	s_waitcnt vmcnt(8)
.Ldw_g1071_a0:
	s_waitcnt lgkmcnt(0)
	s_barrier
	s_setprio 1
	s_waitcnt lgkmcnt(0)
	v_mfma_f32_16x16x32_bf16 v[124:127], v[148:151], v[200:203], v[124:127]
	v_mfma_f32_16x16x32_bf16 v[120:123], v[174:177], v[200:203], v[120:123]
	v_mfma_f32_16x16x32_bf16 v[116:119], v[148:151], v[208:211], v[116:119]
	v_mfma_f32_16x16x32_bf16 v[112:115], v[174:177], v[208:211], v[112:115]
	v_mfma_f32_16x16x32_bf16 v[108:111], v[148:151], v[216:219], v[108:111]
	v_mfma_f32_16x16x32_bf16 v[104:107], v[174:177], v[216:219], v[104:107]
	v_mfma_f32_16x16x32_bf16 v[100:103], v[148:151], v[224:227], v[100:103]
	v_mfma_f32_16x16x32_bf16 v[96:99], v[174:177], v[224:227], v[96:99]
	v_mfma_f32_16x16x32_bf16 v[124:127], v[170:173], v[204:207], v[124:127]
	v_mfma_f32_16x16x32_bf16 v[120:123], v[178:181], v[204:207], v[120:123]
	v_mfma_f32_16x16x32_bf16 v[116:119], v[170:173], v[212:215], v[116:119]
	v_mfma_f32_16x16x32_bf16 v[112:115], v[178:181], v[212:215], v[112:115]
	v_mfma_f32_16x16x32_bf16 v[108:111], v[170:173], v[220:223], v[108:111]
	v_mfma_f32_16x16x32_bf16 v[104:107], v[178:181], v[220:223], v[104:107]
	v_mfma_f32_16x16x32_bf16 v[100:103], v[170:173], v[228:231], v[100:103]
	v_mfma_f32_16x16x32_bf16 v[96:99], v[178:181], v[228:231], v[96:99]
	s_setprio 0
	s_setprio 1
	v_mfma_f32_16x16x32_bf16 v[92:95], v[184:187], v[200:203], v[92:95]
	v_mfma_f32_16x16x32_bf16 v[88:91], v[192:195], v[200:203], v[88:91]
	v_mfma_f32_16x16x32_bf16 v[84:87], v[184:187], v[208:211], v[84:87]
	v_mfma_f32_16x16x32_bf16 v[80:83], v[192:195], v[208:211], v[80:83]
	v_mfma_f32_16x16x32_bf16 v[76:79], v[184:187], v[216:219], v[76:79]
	v_mfma_f32_16x16x32_bf16 v[72:75], v[192:195], v[216:219], v[72:75]
	v_mfma_f32_16x16x32_bf16 v[68:71], v[184:187], v[224:227], v[68:71]
	v_mfma_f32_16x16x32_bf16 v[64:67], v[192:195], v[224:227], v[64:67]
	v_mfma_f32_16x16x32_bf16 v[92:95], v[188:191], v[204:207], v[92:95]
	v_mfma_f32_16x16x32_bf16 v[88:91], v[196:199], v[204:207], v[88:91]
	v_mfma_f32_16x16x32_bf16 v[84:87], v[188:191], v[212:215], v[84:87]
	v_mfma_f32_16x16x32_bf16 v[80:83], v[196:199], v[212:215], v[80:83]
	v_mfma_f32_16x16x32_bf16 v[76:79], v[188:191], v[220:223], v[76:79]
	v_mfma_f32_16x16x32_bf16 v[72:75], v[196:199], v[220:223], v[72:75]
	v_mfma_f32_16x16x32_bf16 v[68:71], v[188:191], v[228:231], v[68:71]
	v_mfma_f32_16x16x32_bf16 v[64:67], v[196:199], v[228:231], v[64:67]
	s_setprio 0
	s_cbranch_vccz .Ldw_g1071_b0
	s_waitcnt vmcnt(8)
; #define PG8_STAGE(bufoff, gbase, voff) do { _Pragma("unroll") for (int _i = 0; _i < 2; ++_i) \
;         __builtin_amdgcn_global_load_lds((const unsigned*)((const char*)(gbase) + (voff)[_i]), (PG8_LAS unsigned*)(lds + (bufoff) + ldsw + _i * 8192), 16, 0, 0); } while (0)
; #define PG8_LDA(dst, b, h) do { _Pragma("unroll") for (int m = 0; m < 4; ++m) _Pragma("unroll") for (int k = 0; k < 2; ++k) dst[m][k] = *(const PG8_LAS bf16x8*)(lds + PG8_SA(b, h) + aoff + m * 2048 + k * 1024); } while (0)
; #define PG8_LDB(dst, b, h) do { _Pragma("unroll") for (int n = 0; n < 2; ++n) _Pragma("unroll") for (int k = 0; k < 2; ++k) dst[n][k] = *(const PG8_LAS bf16x8*)(lds + PG8_SB(b, h) + boff + n * 2048 + k * 1024); } while (0)
; #define PG8_MMA(ai, bj, At, Bt) do { __builtin_amdgcn_s_setprio(1); _Pragma("unroll") for (int m = 0; m < 4; ++m) _Pragma("unroll") for (int n = 0; n < 2; ++n) _Pragma("unroll") for (int k = 0; k < 2; ++k) \
;         acc[ai][bj][m][n] = __builtin_amdgcn_mfma_f32_16x16x32_bf16(Bt[n][k], At[m][k], acc[ai][bj][m][n], 0, 0, 0); __builtin_amdgcn_s_setprio(0); } while (0)
; #define PG8_WAIT_V(n) asm volatile("s_waitcnt vmcnt(" #n ")" ::: "memory")
; #define PG8_WAIT_L(n) asm volatile("s_waitcnt lgkmcnt(" #n ")" ::: "memory")
; #define PG8_BAR __builtin_amdgcn_s_barrier()
; #define PG8_SCHED __builtin_amdgcn_sched_barrier(0)
; template <class Epi, class Sched, bool ALIGN_EPI = false, bool SP2 = false>
; __device__ __forceinline__ void gemm_phase(PG8_LAS unsigned char* lds, const Gemm g, const Sched& S, const Epi& E) {
;     ...
;             PG8_LDA(At, 0, 1); PG8_STAGE(PG8_SB(0, 0), b2, voffB); PG8_STAGE(PG8_SB(0, 1), b2 + hstep, voffB); PG8_STAGE(PG8_SA(0, 0), a2, voffA);
;             PG8_WAIT_V(8); PG8_WAIT_L(0); PG8_BAR; PG8_MMA(1, 0, At, B0); PG8_MMA(1, 1, At, B1); PG8_BAR; PG8_SCHED;
;             PG8_LDB(B0, 1, 0); PG8_LDB(B1, 1, 1); PG8_SCHED; PG8_LDA(At, 1, 0); PG8_STAGE(PG8_SA(0, 1), a2 + hstep, voffA);
.Ldw_g1071_b0:
	s_barrier
	s_add_i32 s59, s52, s33
	v_lshl_add_u64 v[152:153], s[34:35], 0, v[130:131]
	s_mov_b32 m0, s59
	ds_read_b128 v[200:203], v164 offset:16384
	ds_read_b128 v[204:207], v164 offset:17408
	ds_read_b128 v[208:211], v164 offset:18432
	ds_read_b128 v[212:215], v164 offset:19456
	ds_read_b128 v[216:219], v164 offset:20480
	ds_read_b128 v[220:223], v164 offset:21504
	ds_read_b128 v[224:227], v164 offset:22528
	ds_read_b128 v[228:231], v164 offset:23552
	global_load_lds_dwordx4 v[152:153], off
	s_add_i32 m0, s59, 0x2000
	s_add_u32 s60, s34, 0x80000
	v_lshl_add_u64 v[232:233], s[34:35], 0, v[134:135]
	s_addc_u32 s61, s35, 0
	s_add_i32 s59, s53, s33
	global_load_lds_dwordx4 v[232:233], off
	v_lshl_add_u64 v[234:235], s[60:61], 0, v[130:131]
	s_mov_b32 m0, s59
	v_lshl_add_u64 v[236:237], s[36:37], 0, v[132:133]
	global_load_lds_dwordx4 v[234:235], off
	v_lshl_add_u64 v[234:235], s[60:61], 0, v[134:135]
	s_add_i32 m0, s59, 0x2000
	s_nop 0
	global_load_lds_dwordx4 v[234:235], off
	v_lshl_add_u64 v[234:235], s[36:37], 0, v[128:129]
	s_mov_b32 m0, s27
	s_nop 0
	global_load_lds_dwordx4 v[234:235], off
	s_mov_b32 m0, s42
	s_nop 0
	global_load_lds_dwordx4 v[236:237], off
	s_and_b64 vcc, exec, s[16:17]
	s_cbranch_vccnz .Ldw_g1071_a1
	s_waitcnt vmcnt(8)
.Ldw_g1071_a1:
	s_waitcnt lgkmcnt(0)
	s_barrier
	s_setprio 1
	s_waitcnt lgkmcnt(0)
	v_mfma_f32_16x16x32_bf16 v[60:63], v[148:151], v[200:203], v[60:63]
	v_mfma_f32_16x16x32_bf16 v[56:59], v[174:177], v[200:203], v[56:59]
	v_mfma_f32_16x16x32_bf16 v[52:55], v[148:151], v[208:211], v[52:55]
	v_mfma_f32_16x16x32_bf16 v[48:51], v[174:177], v[208:211], v[48:51]
	v_mfma_f32_16x16x32_bf16 v[44:47], v[148:151], v[216:219], v[44:47]
	v_mfma_f32_16x16x32_bf16 v[40:43], v[174:177], v[216:219], v[40:43]
	v_mfma_f32_16x16x32_bf16 v[36:39], v[148:151], v[224:227], v[36:39]
	v_mfma_f32_16x16x32_bf16 v[32:35], v[174:177], v[224:227], v[32:35]
	v_mfma_f32_16x16x32_bf16 v[60:63], v[170:173], v[204:207], v[60:63]
	v_mfma_f32_16x16x32_bf16 v[56:59], v[178:181], v[204:207], v[56:59]
	v_mfma_f32_16x16x32_bf16 v[52:55], v[170:173], v[212:215], v[52:55]
	v_mfma_f32_16x16x32_bf16 v[48:51], v[178:181], v[212:215], v[48:51]
	v_mfma_f32_16x16x32_bf16 v[44:47], v[170:173], v[220:223], v[44:47]
	v_mfma_f32_16x16x32_bf16 v[40:43], v[178:181], v[220:223], v[40:43]
	v_mfma_f32_16x16x32_bf16 v[36:39], v[170:173], v[228:231], v[36:39]
	v_mfma_f32_16x16x32_bf16 v[32:35], v[178:181], v[228:231], v[32:35]
	s_setprio 0
	s_setprio 1
	v_mfma_f32_16x16x32_bf16 v[28:31], v[184:187], v[200:203], v[28:31]
	v_mfma_f32_16x16x32_bf16 v[24:27], v[192:195], v[200:203], v[24:27]
	v_mfma_f32_16x16x32_bf16 v[20:23], v[184:187], v[208:211], v[20:23]
	v_mfma_f32_16x16x32_bf16 v[16:19], v[192:195], v[208:211], v[16:19]
	v_mfma_f32_16x16x32_bf16 v[12:15], v[184:187], v[216:219], v[12:15]
	v_mfma_f32_16x16x32_bf16 v[8:11], v[192:195], v[216:219], v[8:11]
	v_mfma_f32_16x16x32_bf16 v[4:7], v[184:187], v[224:227], v[4:7]
	v_mfma_f32_16x16x32_bf16 v[0:3], v[192:195], v[224:227], v[0:3]
	v_mfma_f32_16x16x32_bf16 v[28:31], v[188:191], v[204:207], v[28:31]
	v_mfma_f32_16x16x32_bf16 v[24:27], v[196:199], v[204:207], v[24:27]
	v_mfma_f32_16x16x32_bf16 v[20:23], v[188:191], v[212:215], v[20:23]
	v_mfma_f32_16x16x32_bf16 v[16:19], v[196:199], v[212:215], v[16:19]
	v_mfma_f32_16x16x32_bf16 v[12:15], v[188:191], v[220:223], v[12:15]
	v_mfma_f32_16x16x32_bf16 v[8:11], v[196:199], v[220:223], v[8:11]
	v_mfma_f32_16x16x32_bf16 v[4:7], v[188:191], v[228:231], v[4:7]
	v_mfma_f32_16x16x32_bf16 v[0:3], v[196:199], v[228:231], v[0:3]
	s_setprio 0
	s_cbranch_vccz .Ldw_g1071_b1
	s_waitcnt vmcnt(8)
.Ldw_g1071_b1:
	s_barrier
	s_add_i32 s59, 0, 0x18000
	v_add_u32_e32 v136, s59, v160
	s_add_i32 s60, 0, 0x1c000
	ds_read_b128 v[148:151], v136
	ds_read_b128 v[170:173], v136 offset:1024
	ds_read_b128 v[174:177], v136 offset:2048
	ds_read_b128 v[178:181], v136 offset:3072
	v_add_u32_e32 v136, s60, v160
	ds_read_b128 v[184:187], v136
	ds_read_b128 v[188:191], v136 offset:1024
	ds_read_b128 v[192:195], v136 offset:2048
	ds_read_b128 v[196:199], v136 offset:3072
	s_add_u32 s36, s36, 0x80000
	s_addc_u32 s37, s37, 0
	s_mov_b32 m0, s43
	v_lshl_add_u64 v[238:239], s[36:37], 0, v[128:129]
	ds_read_b128 v[200:203], v164 offset:32768
	ds_read_b128 v[204:207], v164 offset:33792
	ds_read_b128 v[208:211], v164 offset:34816
	ds_read_b128 v[212:215], v164 offset:35840
	ds_read_b128 v[216:219], v164 offset:36864
	ds_read_b128 v[220:223], v164 offset:37888
	ds_read_b128 v[224:227], v164 offset:38912
	ds_read_b128 v[228:231], v164 offset:39936
	global_load_lds_dwordx4 v[238:239], off
	v_lshl_add_u64 v[238:239], s[36:37], 0, v[132:133]
	s_mov_b32 m0, s44
	s_nop 0
	global_load_lds_dwordx4 v[238:239], off
	s_and_b64 vcc, exec, s[16:17]
	s_cbranch_vccnz .Ldw_g1071_a2
	s_waitcnt vmcnt(8)

; #define PG8_STAGE(bufoff, gbase, voff) do { _Pragma("unroll") for (int _i = 0; _i < 2; ++_i) \
;         __builtin_amdgcn_global_load_lds((const unsigned*)((const char*)(gbase) + (voff)[_i]), (PG8_LAS unsigned*)(lds + (bufoff) + ldsw + _i * 8192), 16, 0, 0); } while (0)
; #define PG8_LDA(dst, b, h) do { _Pragma("unroll") for (int m = 0; m < 4; ++m) _Pragma("unroll") for (int k = 0; k < 2; ++k) dst[m][k] = *(const PG8_LAS bf16x8*)(lds + PG8_SA(b, h) + aoff + m * 2048 + k * 1024); } while (0)
; template <class Epi, class Sched, bool ALIGN_EPI = false, bool SP2 = false>
; __device__ __forceinline__ void gemm_phase(PG8_LAS unsigned char* lds, const Gemm g, const Sched& S, const Epi& E) {
;     ...
;             PG8_LDA(At, 1, 1); PG8_STAGE(PG8_SB(1, 0), b3, voffB); PG8_STAGE(PG8_SB(1, 1), b3 + hstep, voffB); PG8_STAGE(PG8_SA(1, 0), a3, voffA);
.Ldw_g1071_b2:
	s_barrier
	s_add_i32 s36, s59, s33
	v_lshl_add_u64 v[152:153], v[152:153], 0, s[14:15]
	s_mov_b32 m0, s36
	ds_read_b128 v[200:203], v164 offset:49152
	ds_read_b128 v[204:207], v164 offset:50176
	ds_read_b128 v[208:211], v164 offset:51200
	ds_read_b128 v[212:215], v164 offset:52224
	ds_read_b128 v[216:219], v164 offset:53248
	ds_read_b128 v[220:223], v164 offset:54272
	ds_read_b128 v[224:227], v164 offset:55296
	ds_read_b128 v[228:231], v164 offset:56320
	global_load_lds_dwordx4 v[152:153], off
	s_add_i32 m0, s36, 0x2000
	s_add_u32 s34, s34, 0x80080
	v_lshl_add_u64 v[152:153], v[232:233], 0, s[14:15]
	s_addc_u32 s35, s35, 0
	s_add_i32 s36, s60, s33
	global_load_lds_dwordx4 v[152:153], off
	v_lshl_add_u64 v[152:153], s[34:35], 0, v[130:131]
	s_mov_b32 m0, s36
	s_nop 0
	global_load_lds_dwordx4 v[152:153], off
	v_lshl_add_u64 v[152:153], s[34:35], 0, v[134:135]
	s_add_i32 m0, s36, 0x2000
	s_nop 0
	global_load_lds_dwordx4 v[152:153], off
	v_lshl_add_u64 v[152:153], v[234:235], 0, s[14:15]
	s_mov_b32 m0, s46
	s_nop 0
	global_load_lds_dwordx4 v[152:153], off
	v_lshl_add_u64 v[152:153], v[236:237], 0, s[14:15]
	s_mov_b32 m0, s47
	s_nop 0
	global_load_lds_dwordx4 v[152:153], off
	s_and_b64 vcc, exec, s[16:17]
	s_cbranch_vccnz .Ldw_g1071_a3
	s_waitcnt vmcnt(8)

; #define PG8_STAGE(bufoff, gbase, voff) do { _Pragma("unroll") for (int _i = 0; _i < 2; ++_i) \
;         __builtin_amdgcn_global_load_lds((const unsigned*)((const char*)(gbase) + (voff)[_i]), (PG8_LAS unsigned*)(lds + (bufoff) + ldsw + _i * 8192), 16, 0, 0); } while (0)
; #define PG8_LDA(dst, b, h) do { _Pragma("unroll") for (int m = 0; m < 4; ++m) _Pragma("unroll") for (int k = 0; k < 2; ++k) dst[m][k] = *(const PG8_LAS bf16x8*)(lds + PG8_SA(b, h) + aoff + m * 2048 + k * 1024); } while (0)
; #define PG8_WAIT_V(n) asm volatile("s_waitcnt vmcnt(" #n ")" ::: "memory")
; #define PG8_WAIT_L(n) asm volatile("s_waitcnt lgkmcnt(" #n ")" ::: "memory")
; template <class Epi, class Sched, bool ALIGN_EPI = false, bool SP2 = false>
; __device__ __forceinline__ void gemm_phase(PG8_LAS unsigned char* lds, const Gemm g, const Sched& S, const Epi& E) {
;     ...
;         for (int t = 0; t < nt; t += 2) {
;             const bool last = (t == nt - 2);
;             const char* a1 = cA + (size_t)(t + 1) * kstep;
;             const char* a2 = last ? nA : cA + (size_t)(t + 2) * kstep; const char* b2 = last ? nB : cB + (size_t)(t + 2) * kstep;
;             const char* a3 = a2 + kstep; const char* b3 = b2 + kstep;
;             if (last && has_next) S.a_ready(nxt);
;             if constexpr (SP2) {
;             PG8_LDB(B0, 0, 0); PG8_LDB(B1, 0, 1); PG8_SCHED; PG8_LDA(At, 0, 0); PG8_STAGE(PG8_SA(1, 1), a1 + hstep, voffA);
;             PG8_WAIT_V(8); PG8_WAIT_L(0); PG8_BAR; PG8_MMA(0, 0, At, B0); PG8_MMA(0, 1, At, B1); PG8_BAR; PG8_SCHED;
;             PG8_LDA(At, 0, 1); PG8_STAGE(PG8_SB(0, 0), b2, voffB); PG8_STAGE(PG8_SB(0, 1), b2 + hstep, voffB); PG8_STAGE(PG8_SA(0, 0), a2, voffA);
;             PG8_WAIT_V(8); PG8_WAIT_L(0); PG8_BAR; PG8_MMA(1, 0, At, B0); PG8_MMA(1, 1, At, B1); PG8_BAR; PG8_SCHED;
;             PG8_LDB(B0, 1, 0); PG8_LDB(B1, 1, 1); PG8_SCHED; PG8_LDA(At, 1, 0); PG8_STAGE(PG8_SA(0, 1), a2 + hstep, voffA);
;             PG8_WAIT_V(8); PG8_WAIT_L(0); PG8_BAR; PG8_MMA(0, 0, At, B0); PG8_MMA(0, 1, At, B1); PG8_BAR; PG8_SCHED;
;             PG8_LDA(At, 1, 1); PG8_STAGE(PG8_SB(1, 0), b3, voffB); PG8_STAGE(PG8_SB(1, 1), b3 + hstep, voffB); PG8_STAGE(PG8_SA(1, 0), a3, voffA);
;             PG8_WAIT_V(8); PG8_WAIT_L(0); PG8_BAR; PG8_MMA(1, 0, At, B0); PG8_MMA(1, 1, At, B1); PG8_BAR; PG8_SCHED;
;     ...
;         if constexpr (ALIGN_EPI) { if (wr == 0) PG8_BAR; }
.Ldw_g1071_b3:
	s_barrier
	s_add_i32 s58, s58, 2
	s_add_u32 s30, s30, 0x100
	s_addc_u32 s31, s31, 0
	s_add_u32 s56, s56, 0x100
	s_addc_u32 s57, s57, 0
	s_cmp_gt_u32 s58, 29
	s_cbranch_scc0 .LBB0_1071
	s_and_b64 vcc, exec, s[16:17]
	s_cbranch_vccz .LBB0_1074
	s_barrier
